# v100 without the L2 write-back in SEAM0's leader path (every P0 store is write-through, nothing is dirty there)
# baseline (speedup 1.0000x reference)
; __device__ __forceinline__ unsigned xb_add(unsigned* p, unsigned v) { return __hip_atomic_fetch_add(p, v, __ATOMIC_RELAXED, __HIP_MEMORY_SCOPE_AGENT); }
; __device__ __forceinline__ void xcd_barrier(const XcdBarrier& b) {
;     ...
;         if (old + 1u == (gen + 1u) * nloc) {
;             __builtin_amdgcn_fence(__ATOMIC_RELEASE, "agent");
;             asm volatile("s_waitcnt vmcnt(0)" ::: "memory");
;             const unsigned og = xb_add(&bar[XB_TOP], 1u);
;             const unsigned tg = og / nx;
;             if (og + 1u == (tg + 1u) * nx) xb_add(&bar[XB_TOPGEN], 1u);
.LBB0_95:
	s_andn2_saveexec_b64 s[8:9], s[8:9]
	s_cbranch_execz .LBB0_115
	s_mov_b64 s[8:9], exec
	s_waitcnt lgkmcnt(0)
	s_waitcnt vmcnt(0)
	v_mbcnt_lo_u32_b32 v1, s8, 0
	v_mbcnt_hi_u32_b32 v1, s9, v1
	v_cmp_eq_u32_e32 vcc, 0, v1
	s_and_saveexec_b64 s[10:11], vcc
	s_cbranch_execz .LBB0_98
	s_bcnt1_i32_b64 s8, s[8:9]
	v_mov_b32_e32 v2, 0x1f03000
	v_mov_b32_e32 v3, s8
	global_atomic_add v2, v2, v3, s[78:79] offset:1024 sc0
